# pair GEMM phase prologue: first-tile rsqrt cache filled during the first stage-load wait (4 waves of a row half share the work)
# baseline (speedup 1.0000x reference)
.LBB0_131:
	s_mov_b32 s52, -1
	v_writelane_b32 v248, s52, 41
	s_lshl_b32 s36, s11, 6
	v_mov_b32_e32 v9, v199
	v_readlane_b32 s1, v251, 0
	s_cmp_ge_i32 s1, s36
	v_readfirstlane_b32 s19, v9
	s_mov_b32 s55, s44
	s_cbranch_scc1 .LBB0_151
	v_lshlrev_b32_e32 v0, 4, v9
	s_waitcnt lgkmcnt(0)
	v_add_u32_e32 v1, 0x2000, v0
	v_ashrrev_i32_e32 v2, 31, v1
	v_lshrrev_b32_e32 v2, 22, v2
	v_add_u32_e32 v2, v1, v2
	v_ashrrev_i32_e32 v8, 10, v2
	v_mul_i32_i24_e32 v2, 0x400, v8
	v_sub_u32_e32 v1, v1, v2
	v_lshrrev_b32_e32 v2, 4, v1
	v_bitop3_b32 v1, v2, v1, 32 bitop3:0x6c
	v_ashrrev_i32_e32 v2, 31, v1
	v_lshrrev_b32_e32 v2, 26, v2
	v_add_u32_e32 v2, v1, v2
	v_lshlrev_b32_e32 v3, 3, v8
	v_ashrrev_i32_e32 v10, 6, v2
	v_and_b32_e32 v3, -16, v3
	v_add_u32_e32 v3, v10, v3
	v_and_b32_e32 v4, 3, v10
	s_mov_b32 s2, 0x1fffe0
	v_lshrrev_b32_e32 v5, 2, v3
	v_lshlrev_b32_e32 v6, 1, v3
	v_and_b32_e32 v2, 0xc0, v2
	v_and_or_b32 v4, v3, s2, v4
	v_and_b32_e32 v5, 4, v5
	v_and_b32_e32 v6, 24, v6
	v_sub_u32_e32 v1, v1, v2
	v_or3_b32 v4, v4, v5, v6
	v_lshlrev_b32_e32 v5, 5, v8
	v_ashrrev_i16_sdwa v1, v223, sext(v1) dst_sel:DWORD dst_unused:UNUSED_PAD src0_sel:DWORD src1_sel:BYTE_0
	v_and_b32_e32 v5, 32, v5
	v_bfe_i32 v11, v1, 0, 16
	v_add_lshl_u32 v1, v5, v11, 1
	s_waitcnt vmcnt(0)
	v_lshl_add_u32 v152, v4, 11, v1
	v_lshl_add_u32 v154, v3, 11, v1
	v_bfe_i32 v1, v9, 27, 1
	v_lshrrev_b32_e32 v1, 22, v1
	v_add_u32_e32 v1, v0, v1
	v_and_b32_e32 v1, 0xfffffc00, v1
	v_sub_u32_e32 v0, v0, v1
	v_lshrrev_b32_e32 v1, 4, v0
	v_ashrrev_i32_e32 v2, 31, v9
	v_bitop3_b32 v0, v1, v0, 32 bitop3:0x6c
	v_lshrrev_b32_e32 v2, 26, v2
	v_ashrrev_i32_e32 v1, 31, v0
	v_add_u32_e32 v2, v9, v2
	v_lshrrev_b32_e32 v1, 26, v1
	v_ashrrev_i32_e32 v13, 6, v2
	v_add_u32_e32 v1, v0, v1
	v_lshlrev_b32_e32 v2, 3, v13
	v_ashrrev_i32_e32 v12, 6, v1
	v_and_b32_e32 v2, -16, v2
	v_add_u32_e32 v2, v12, v2
	v_and_b32_e32 v3, 3, v12
	s_ashr_i32 s21, s19, 6
	v_and_or_b32 v3, v2, s2, v3
	s_lshl_b32 s2, s11, 3
	v_readlane_b32 s12, v250, 5
	s_ashr_i32 s20, s19, 8
	s_lshl_b32 s1, s21, 10
	s_or_b32 s3, s2, 1
	v_readlane_b32 s13, v250, 6
	s_and_b64 s[12:13], s[12:13], exec
	v_and_b32_e32 v1, 0xc0, v1
	s_cselect_b32 s12, s3, s2
	s_lshl_b32 s9, s11, 2
	v_sub_u32_e32 v0, v0, v1
	v_cvt_f32_u32_e32 v1, s9
	v_lshrrev_b32_e32 v4, 2, v2
	v_lshlrev_b32_e32 v5, 1, v2
	v_and_b32_e32 v4, 4, v4
	v_and_b32_e32 v5, 24, v5
	v_rcp_iflag_f32_e32 v1, v1
	v_or3_b32 v3, v3, v4, v5
	v_lshlrev_b32_e32 v4, 5, v13
	v_ashrrev_i16_sdwa v0, v223, sext(v0) dst_sel:DWORD dst_unused:UNUSED_PAD src0_sel:DWORD src1_sel:BYTE_0
	v_and_b32_e32 v4, 32, v4
	v_bfe_i32 v14, v0, 0, 16
	v_add_lshl_u32 v0, v4, v14, 1
	v_lshl_add_u32 v196, v3, 11, v0
	v_lshl_add_u32 v156, v2, 11, v0
	v_mul_f32_e32 v0, 0x4f7ffffe, v1
	v_cvt_u32_f32_e32 v0, v0
	v_readlane_b32 s11, v250, 12
	s_mul_i32 s11, s12, s11
	v_readlane_b32 s12, v250, 7
	s_add_i32 s12, s11, s12
	s_sub_i32 s11, 0, s9
	v_readfirstlane_b32 s15, v0
	s_mul_i32 s11, s11, s15
	s_mul_hi_u32 s11, s15, s11
	s_abs_i32 s14, s12
	s_add_i32 s11, s15, s11
	s_mul_hi_u32 s15, s14, s11
	s_mul_i32 s17, s15, s9
	s_sub_i32 s14, s14, s17
	s_ashr_i32 s13, s12, 31
	s_add_i32 s17, s15, 1
	s_sub_i32 s18, s14, s9
	s_cmp_ge_u32 s14, s9
	s_cselect_b32 s15, s17, s15
	s_cselect_b32 s14, s18, s14
	s_add_i32 s17, s15, 1
	s_cmp_ge_u32 s14, s9
	s_cselect_b32 s14, s17, s15
	s_xor_b32 s14, s14, s13
	s_sub_i32 s13, s14, s13
	s_mul_i32 s14, s13, s9
	s_sub_i32 s22, s12, s14
	s_and_b32 s14, s13, 1
	s_mul_i32 s14, s14, s9
	s_add_i32 s22, s22, s14
	s_lshr_b32 s14, s13, 1
	s_lshl_b32 s14, s14, 3
	s_lshr_b32 s18, s22, 3
	s_and_b32 s12, s22, 7
	s_add_i32 s34, s14, s12
	s_ashr_i32 s35, s34, 31
	s_bfe_i64 s[14:15], s[18:19], 0x100000
	s_lshl_b64 s[12:13], s[34:35], 19
	s_lshl_b64 s[14:15], s[14:15], 19
	s_add_u32 s44, s6, s14
	s_addc_u32 s45, s7, s15
	s_add_i32 s14, s1, 0
	v_and_b32_e32 v174, 15, v199
	v_lshrrev_b32_e32 v175, 8, v199
	v_readlane_b32 s22, v249, 56
	v_lshl_or_b32 v174, v175, 6, v174
	v_readlane_b32 s23, v249, 57
	v_bfe_u32 v176, v199, 4, 2
	v_lshl_add_u32 v174, s34, 8, v174
	v_lshlrev_b32_e32 v176, 4, v176
	v_mov_b32_e32 v177, 0
	v_lshl_add_u64 v[178:179], s[22:23], 0, v[176:177]
	s_bfe_u32 s22, s19, 0x20006
	s_and_b32 s23, s22, 1
	s_lshl_b32 s23, s23, 5
	s_lshr_b32 s22, s22, 1
	s_lshl_b32 s22, s22, 7
	s_add_i32 s22, s22, s23
	v_add_u32_e32 v176, s22, v174
	v_lshlrev_b32_e32 v176, 6, v176
	v_lshl_add_u64 v[180:181], v[178:179], 0, v[176:177]
	global_load_dwordx4 v[128:131], v[180:181], off
	global_load_dwordx4 v[132:135], v[180:181], off offset:1024
	s_add_i32 m0, s14, 0x10000
	v_mov_b32_e32 v153, v197
	global_load_lds_dwordx4 v196, s[44:45]
	s_add_i32 m0, s14, 0x12000
	s_add_u32 s22, s44, 0x40000
	global_load_lds_dwordx4 v152, s[44:45]
	s_addc_u32 s23, s45, 0
	s_add_i32 m0, s14, 0x14000
	v_mov_b32_e32 v157, v197
	global_load_lds_dwordx4 v196, s[22:23]
	s_add_i32 m0, s14, 0x16000
	s_add_u32 s40, s80, s12
	s_addc_u32 s41, s81, s13
	s_add_i32 s15, s14, 0x2000
	global_load_lds_dwordx4 v152, s[22:23]
	s_mov_b32 m0, s14
	s_add_u32 s12, s40, 0x40000
	global_load_lds_dwordx4 v156, s[40:41]
	s_mov_b32 m0, s15
	s_addc_u32 s13, s41, 0
	s_add_i32 s17, s14, 0x4000
	global_load_lds_dwordx4 v154, s[40:41]
	s_mov_b32 m0, s17
	s_add_i32 s26, s14, 0x6000
	global_load_lds_dwordx4 v156, s[12:13]
	s_mov_b32 m0, s26
	v_mov_b32_e32 v155, v197
	global_load_lds_dwordx4 v154, s[12:13]
	s_cmp_eq_u32 s20, 1
	s_mov_b32 s56, s30
	v_lshl_add_u64 v[6:7], s[44:45], 0, v[196:197]
	v_lshl_add_u64 v[4:5], s[44:45], 0, v[152:153]
	v_lshl_add_u64 v[0:1], s[40:41], 0, v[156:157]
	s_cselect_b64 s[12:13], -1, 0
	s_cmp_lg_u32 s20, 1
	v_lshl_add_u64 v[2:3], s[40:41], 0, v[154:155]
	s_cbranch_scc1 .LBB0_134
	s_barrier
.LBB0_134:
	s_lshl_b32 s21, s21, 5
	s_and_b32 s21, s21, 0x60
	s_add_i32 m0, s14, 0x18000
	v_lshl_add_u64 v[6:7], v[6:7], 0, s[88:89]
	s_lshl_b32 s24, s20, 13
	s_lshl_b32 s25, s21, 7
	s_waitcnt vmcnt(8)
	v_mov_b32_e32 v212, 0x358637bd
	v_add_f32_e32 v128, v129, v128
	v_add_f32_e32 v130, v130, v131
	v_add_f32_e32 v204, v128, v130
	v_add_f32_e32 v132, v133, v132
	v_add_f32_e32 v134, v134, v135
	v_add_f32_e32 v205, v132, v134
	v_mov_b32_e32 v180, v204
	s_nop 1
	v_permlane16_swap_b32_e32 v204, v180
	v_add_f32_e32 v204, v204, v180
	v_mov_b32_e32 v180, v204
	s_nop 1
	v_permlane32_swap_b32_e32 v204, v180
	v_add_f32_e32 v204, v204, v180
	v_mov_b32_e32 v180, v205
	s_nop 1
	v_permlane16_swap_b32_e32 v205, v180
	v_add_f32_e32 v205, v205, v180
	v_mov_b32_e32 v180, v205
	s_nop 1
	v_permlane32_swap_b32_e32 v205, v180
	v_add_f32_e32 v205, v205, v180
	v_fmamk_f32 v204, v204, 0x3a800000, v212
	v_mul_f32_e32 v180, 0x4b800000, v204
	v_cmp_gt_f32_e32 vcc, s39, v204
	s_nop 1
	v_cndmask_b32_e32 v204, v204, v180, vcc
	v_rsq_f32_e32 v204, v204
	s_nop 0
	v_mul_f32_e32 v180, 0x45800000, v204
	v_cndmask_b32_e32 v204, v204, v180, vcc
	v_fmamk_f32 v205, v205, 0x3a800000, v212
	v_mul_f32_e32 v180, 0x4b800000, v205
	v_cmp_gt_f32_e32 vcc, s39, v205
	s_nop 1
	v_cndmask_b32_e32 v205, v205, v180, vcc
	v_rsq_f32_e32 v205, v205
	s_nop 0
	v_mul_f32_e32 v180, 0x45800000, v205
	v_cndmask_b32_e32 v205, v205, v180, vcc
	v_lshrrev_b32_e32 v180, 8, v199
	v_and_b32_e32 v181, 15, v199
	v_lshlrev_b32_e32 v180, 11, v180
	v_lshl_add_u32 v181, v181, 2, v180
	s_bfe_u32 s22, s19, 0x20006
	s_lshl_b32 s22, s22, 7
	s_add_i32 s22, s22, 0x20040
	v_add_u32_e32 v181, s22, v181
	ds_write_b32 v181, v204
	ds_write_b32 v181, v205 offset:64
	ds_write_b32 v181, v204 offset:512
	ds_write_b32 v181, v205 offset:576
	ds_write_b32 v181, v204 offset:1024
	ds_write_b32 v181, v205 offset:1088
	ds_write_b32 v181, v204 offset:1536
	ds_write_b32 v181, v205 offset:1600
	v_writelane_b32 v248, s34, 41
	s_waitcnt vmcnt(2)
	s_barrier
	global_load_lds_dwordx4 v[6:7], off
	v_lshl_add_u64 v[4:5], v[4:5], 0, s[88:89]
	s_add_i32 m0, s14, 0x1a000
	s_add_i32 s27, s14, 0x8000
	s_add_i32 s28, s14, 0xa000
	global_load_lds_dwordx4 v[4:5], off
	v_lshl_add_u64 v[0:1], v[0:1], 0, s[88:89]
	s_mov_b32 m0, s27
	s_add_u32 s22, s44, 0x40080
	global_load_lds_dwordx4 v[0:1], off
	v_lshl_add_u64 v[0:1], v[2:3], 0, s[88:89]
	s_mov_b32 m0, s28
	s_addc_u32 s23, s45, 0
	global_load_lds_dwordx4 v[0:1], off
	s_add_i32 m0, s14, 0x1c000
	v_lshl_add_u64 v[0:1], s[22:23], 0, v[196:197]
	global_load_lds_dwordx4 v[0:1], off
	v_lshl_add_u64 v[0:1], s[22:23], 0, v[152:153]
	s_add_i32 m0, s14, 0x1e000
	v_bfe_u32 v2, v9, 4, 2
	global_load_lds_dwordx4 v[0:1], off
	v_and_b32_e32 v1, 15, v9
	v_lshlrev_b32_e32 v0, 4, v2
	v_lshlrev_b32_e32 v3, 2, v9
	v_lshl_or_b32 v184, s20, 6, v1
	v_lshl_or_b32 v1, v1, 6, v0
	v_and_b32_e32 v3, 32, v3
	v_readlane_b32 s22, v249, 56
	v_bitop3_b32 v4, v1, s24, v3 bitop3:0xde
	v_bitop3_b32 v185, v1, s25, v3 bitop3:0xde
	v_mov_b32_e32 v1, v197
	v_readlane_b32 s23, v249, 57
	s_cmpk_lt_u32 s19, 0x100
	s_sext_i32_i16 s33, s18
	v_lshl_add_u64 v[158:159], s[22:23], 0, v[0:1]
	v_lshlrev_b32_e32 v0, 14, v13
	v_and_b32_e32 v0, 0xffff8000, v0
	v_lshl_add_u32 v0, v12, 11, v0
	v_and_b32_e32 v1, 1, v13
	v_lshl_or_b32 v0, v1, 6, v0
	v_lshl_add_u32 v160, v14, 1, v0
	v_lshlrev_b32_e32 v0, 14, v8
	v_and_b32_e32 v0, 0xffff8000, v0
	v_lshl_add_u32 v0, v10, 11, v0
	v_and_b32_e32 v1, 1, v8
	v_lshl_or_b32 v0, v1, 6, v0
	s_cselect_b64 s[18:19], -1, 0
	v_lshl_or_b32 v186, v2, 3, s21
	v_mov_b32_e32 v161, v197
	v_lshl_add_u32 v162, v11, 1, v0
	v_mov_b32_e32 v163, v197
	s_mov_b32 s29, 0
	v_add_u32_e32 v187, 0, v4
	v_mov_b64_e32 v[164:165], s[36:37]
	s_branch .LBB0_137
